# attention trims: max tree without self-max canonicalisation, 2 waits for the 8 K fragments, tile loads through SGPR bases (no 64-bit VALU address math)
# speedup vs baseline: 1.0094x; 1.0094x over previous
.LBB0_227:
	s_lshl_b32 s4, s59, 11
	s_and_b32 s5, s4, 0x1000000
	s_lshl_b32 s4, s36, 4
	s_and_b32 s28, s4, 0x700
	v_lshl_or_b32 v96, v148, 1, s28
	v_or_b32_e32 v96, s5, v96
	v_mov_b32_e32 v97, v209
	s_lshl_b32 s21, s21, 9
	s_mov_b32 s65, 2
	s_add_i32 s66, s8, 2
	s_mov_b32 s4, 1
	v_lshl_add_u64 v[174:175], v[170:171], 0, v[96:97]
	v_subrev_u32_e32 v204, s21, v194
	s_add_i32 s33, s61, s8
	s_mov_b32 s87, 0
	s_movk_i32 s68, 0xff00
	v_readfirstlane_b32 s80, v174
	v_readfirstlane_b32 s81, v175
	s_nop 1
	v_subrev_u32_e32 v232, s80, v174
	v_add_u32_e32 v233, 0x10000, v232
	s_add_u32 s92, s80, 0xf5ff0000
	s_addc_u32 s93, s81, -1
	s_add_u32 s80, s80, 0xffff0000
	s_addc_u32 s81, s81, -1
	s_waitcnt lgkmcnt(0)
	s_barrier
	s_and_b64 vcc, exec, s[16:17]
	s_cbranch_vccnz .LBB0_228
	s_cmp_lt_i32 s9, 1
	s_cbranch_scc1 .LBB0_228
	s_movk_i32 s5, 0x4400
	v_add_u32_e32 v205, s5, v192
	ds_read_b128 v[96:99], v205 offset:8704
	ds_read_b128 v[100:103], v205 offset:8736
	ds_read_b128 v[104:107], v205 offset:8768
	ds_read_b128 v[108:111], v205 offset:8800
	ds_read_b128 v[176:179], v205
	ds_read_b128 v[180:183], v205 offset:32
	ds_read_b128 v[184:187], v205 offset:64
	ds_read_b128 v[188:191], v205 offset:96
	s_waitcnt lgkmcnt(7)
	v_mfma_f32_32x32x16_bf16 v[80:95], v[96:99], v[112:115], v[64:79]
	s_waitcnt lgkmcnt(6)
	v_mfma_f32_32x32x16_bf16 v[80:95], v[100:103], v[116:119], v[80:95]
	s_waitcnt lgkmcnt(5)
	v_mfma_f32_32x32x16_bf16 v[80:95], v[104:107], v[120:123], v[80:95]
	s_waitcnt lgkmcnt(4)
	v_mfma_f32_32x32x16_bf16 v[80:95], v[108:111], v[124:127], v[80:95]
	s_waitcnt lgkmcnt(3)
	v_mfma_f32_32x32x16_bf16 v[96:111], v[176:179], v[112:115], v[64:79]
	s_waitcnt lgkmcnt(2)
	v_mfma_f32_32x32x16_bf16 v[96:111], v[180:183], v[116:119], v[96:111]
	s_waitcnt lgkmcnt(1)
	v_mfma_f32_32x32x16_bf16 v[96:111], v[184:187], v[120:123], v[96:111]
	s_waitcnt lgkmcnt(0)
	v_mfma_f32_32x32x16_bf16 v[96:111], v[188:191], v[124:127], v[96:111]
	s_cmp_gt_i32 s33, 2
	s_cbranch_scc1 .LBB0_228
	s_waitcnt lgkmcnt(0)
	v_add_u32_e32 v205, s68, v204
	v_add_u32_e32 v176, 0x17d00, v205
	v_add_u32_e32 v178, 0x17d80, v205
	ds_read2_b32 v[176:177], v176 offset1:1
	ds_read2_b32 v[178:179], v178 offset1:1
	v_add_u32_e32 v180, 0x17d08, v205
	v_add_u32_e32 v182, 0x17d88, v205
	v_add_u32_e32 v184, 0x17d20, v205
	v_add_u32_e32 v186, 0x17da0, v205
	v_add_u32_e32 v188, 0x17d28, v205
	v_add_u32_e32 v190, 0x17da8, v205
	v_add_u32_e32 v206, 0x17d40, v205
	v_add_u32_e32 v210, 0x17dc0, v205
	v_add_u32_e32 v212, 0x17d48, v205
	v_add_u32_e32 v221, 0x17dc8, v205
	ds_read2_b32 v[180:181], v180 offset1:1
	ds_read2_b32 v[182:183], v182 offset1:1
	ds_read2_b32 v[184:185], v184 offset1:1
	ds_read2_b32 v[186:187], v186 offset1:1
	ds_read2_b32 v[188:189], v188 offset1:1
	ds_read2_b32 v[190:191], v190 offset1:1
	ds_read2_b32 v[206:207], v206 offset1:1
	ds_read2_b32 v[210:211], v210 offset1:1
	ds_read2_b32 v[212:213], v212 offset1:1
	ds_read2_b32 v[224:225], v221 offset1:1
	v_add_u32_e32 v221, 0x17d60, v205
	v_add_u32_e32 v223, 0x17de0, v205
	ds_read2_b32 v[226:227], v221 offset1:1
	ds_read2_b32 v[228:229], v223 offset1:1
	v_add_u32_e32 v221, 0x17d68, v205
	v_add_u32_e32 v205, 0x17de8, v205
	ds_read2_b32 v[230:231], v221 offset1:1
	s_waitcnt lgkmcnt(14)
	v_pk_add_f32 v[96:97], v[96:97], v[176:177]
	ds_read2_b32 v[176:177], v205 offset1:1
	s_waitcnt lgkmcnt(3)
	v_pk_add_f32 v[108:109], v[108:109], v[226:227]
	v_pk_add_f32 v[106:107], v[106:107], v[212:213]
	s_waitcnt lgkmcnt(1)
	v_pk_add_f32 v[110:111], v[110:111], v[230:231]
	v_pk_add_f32 v[104:105], v[104:105], v[206:207]
	v_pk_add_f32 v[102:103], v[102:103], v[188:189]
	v_pk_add_f32 v[100:101], v[100:101], v[184:185]
	v_pk_add_f32 v[98:99], v[98:99], v[180:181]
	s_waitcnt lgkmcnt(0)
	v_pk_add_f32 v[94:95], v[94:95], v[176:177]
	v_pk_add_f32 v[92:93], v[92:93], v[228:229]
	v_pk_add_f32 v[90:91], v[90:91], v[224:225]
	v_pk_add_f32 v[88:89], v[88:89], v[210:211]
	v_pk_add_f32 v[86:87], v[86:87], v[190:191]
	v_pk_add_f32 v[84:85], v[84:85], v[186:187]
	v_pk_add_f32 v[82:83], v[82:83], v[182:183]
	v_pk_add_f32 v[80:81], v[80:81], v[178:179]
	s_nop 0
.LBB0_228:
	s_add_i32 s86, s65, -1
	s_bitcmp0_b32 s86, 0
	s_mov_b32 s69, s4
	s_cselect_b32 s28, 0x4400, 0
	s_cselect_b32 s5, 0, 0x4400
	s_mul_i32 s29, s69, 0x5000
	s_addk_i32 s29, 0x5000
	s_cmp_lg_u32 s69, 2
	s_cselect_b32 s29, s29, 0
	s_and_b64 vcc, exec, s[16:17]
	s_cbranch_vccnz .Latt_a
	s_cmp_ge_u32 s65, s66
	s_cbranch_scc1 .Latt_b_sm
	v_add_u32_e32 v176, s28, v157
	s_waitcnt vmcnt(3)
	ds_write_b128 v176, v[128:131]
	v_add_u32_e32 v176, s29, v159
	s_waitcnt vmcnt(2)
	ds_write_b128 v176, v[132:135] offset:34816
	v_add_u32_e32 v176, s28, v161
	s_waitcnt vmcnt(1)
	ds_write_b128 v176, v[136:139]
	v_add_u32_e32 v176, s29, v163
	s_cmp_ge_u32 s86, s8
	s_waitcnt vmcnt(0)
	ds_write_b128 v176, v[140:143] offset:34816
	s_cbranch_scc1 .Latt_b_sm
	global_load_dwordx4 v[128:131], v232, s[92:93]
	global_load_dwordx4 v[132:135], v232, s[80:81]
	global_load_dwordx4 v[136:139], v233, s[92:93]
	global_load_dwordx4 v[140:143], v233, s[80:81]
.Latt_b_sm:
	s_cmp_gt_i32 s86, s9
	s_cbranch_scc1 .Latt_b_bar
	v_max_f32_e32 v176, v96, v80
	v_max3_f32 v177, v81, v98, v82
	v_max3_f32 v176, v176, v97, v99
	v_max3_f32 v177, v177, v100, v84
	v_max3_f32 v176, v176, v83, v101
	v_max3_f32 v177, v177, v102, v86
	v_max3_f32 v176, v176, v85, v103
	v_max3_f32 v177, v177, v104, v88
	v_max3_f32 v176, v176, v87, v105
	v_max3_f32 v177, v177, v106, v90
	v_max3_f32 v176, v176, v89, v107
	v_max3_f32 v177, v177, v108, v92
	v_max3_f32 v176, v176, v91, v109
	v_max3_f32 v177, v177, v110, v94
	v_max3_f32 v176, v176, v93, v111
	v_max3_f32 v176, v176, v95, v177
	v_mov_b32_e32 v177, v176
	s_nop 1
	v_permlane32_swap_b32_e32 v176, v177
	v_max_f32_e32 v176, v176, v177
	v_cmp_lt_f32_e32 vcc, 0x41000000, v176
	s_cbranch_vccz .Latt_b_exp
	v_max_f32_e32 v64, v176, v176
	v_max_f32_e32 v66, 0, v64
	v_exp_f32_e64 v176, -v66
	v_add_f32_e32 v173, v173, v66
	v_xor_b32_e32 v64, 0x80000000, v173
	v_pk_add_f32 v[96:97], v[96:97], v[66:67] op_sel_hi:[1,0] neg_lo:[0,1] neg_hi:[0,1]
	v_pk_add_f32 v[80:81], v[80:81], v[66:67] op_sel_hi:[1,0] neg_lo:[0,1] neg_hi:[0,1]
	v_pk_add_f32 v[98:99], v[98:99], v[66:67] op_sel_hi:[1,0] neg_lo:[0,1] neg_hi:[0,1]
	v_pk_add_f32 v[82:83], v[82:83], v[66:67] op_sel_hi:[1,0] neg_lo:[0,1] neg_hi:[0,1]
	v_pk_add_f32 v[100:101], v[100:101], v[66:67] op_sel_hi:[1,0] neg_lo:[0,1] neg_hi:[0,1]
	v_pk_add_f32 v[84:85], v[84:85], v[66:67] op_sel_hi:[1,0] neg_lo:[0,1] neg_hi:[0,1]
	v_pk_add_f32 v[102:103], v[102:103], v[66:67] op_sel_hi:[1,0] neg_lo:[0,1] neg_hi:[0,1]
	v_pk_add_f32 v[86:87], v[86:87], v[66:67] op_sel_hi:[1,0] neg_lo:[0,1] neg_hi:[0,1]
	v_pk_add_f32 v[104:105], v[104:105], v[66:67] op_sel_hi:[1,0] neg_lo:[0,1] neg_hi:[0,1]
	v_pk_add_f32 v[88:89], v[88:89], v[66:67] op_sel_hi:[1,0] neg_lo:[0,1] neg_hi:[0,1]
	v_pk_add_f32 v[106:107], v[106:107], v[66:67] op_sel_hi:[1,0] neg_lo:[0,1] neg_hi:[0,1]
	v_pk_add_f32 v[90:91], v[90:91], v[66:67] op_sel_hi:[1,0] neg_lo:[0,1] neg_hi:[0,1]
	v_pk_add_f32 v[108:109], v[108:109], v[66:67] op_sel_hi:[1,0] neg_lo:[0,1] neg_hi:[0,1]
	v_pk_add_f32 v[92:93], v[92:93], v[66:67] op_sel_hi:[1,0] neg_lo:[0,1] neg_hi:[0,1]
	v_pk_add_f32 v[110:111], v[110:111], v[66:67] op_sel_hi:[1,0] neg_lo:[0,1] neg_hi:[0,1]
	v_pk_add_f32 v[94:95], v[94:95], v[66:67] op_sel_hi:[1,0] neg_lo:[0,1] neg_hi:[0,1]
	v_mov_b32_e32 v65, v64
	v_mov_b32_e32 v66, v64
	v_mov_b32_e32 v67, v64
	v_mov_b32_e32 v68, v64
	v_mov_b32_e32 v69, v64
	v_mov_b32_e32 v70, v64
	v_mov_b32_e32 v71, v64
	v_mov_b32_e32 v72, v64
	v_mov_b32_e32 v73, v64
	v_mov_b32_e32 v74, v64
	v_mov_b32_e32 v75, v64
	v_mov_b32_e32 v76, v64
	v_mov_b32_e32 v77, v64
	v_mov_b32_e32 v78, v64
	v_mov_b32_e32 v79, v64
	v_pk_mul_f32 v[46:47], v[46:47], v[176:177] op_sel_hi:[1,0]
	v_pk_mul_f32 v[44:45], v[44:45], v[176:177] op_sel_hi:[1,0]
	v_pk_mul_f32 v[42:43], v[42:43], v[176:177] op_sel_hi:[1,0]
	v_pk_mul_f32 v[40:41], v[40:41], v[176:177] op_sel_hi:[1,0]
	v_pk_mul_f32 v[38:39], v[38:39], v[176:177] op_sel_hi:[1,0]
	v_pk_mul_f32 v[36:37], v[36:37], v[176:177] op_sel_hi:[1,0]
	v_pk_mul_f32 v[34:35], v[34:35], v[176:177] op_sel_hi:[1,0]
	v_pk_mul_f32 v[32:33], v[32:33], v[176:177] op_sel_hi:[1,0]
	v_pk_mul_f32 v[30:31], v[30:31], v[176:177] op_sel_hi:[1,0]
	v_pk_mul_f32 v[28:29], v[28:29], v[176:177] op_sel_hi:[1,0]
	v_pk_mul_f32 v[26:27], v[26:27], v[176:177] op_sel_hi:[1,0]
	v_pk_mul_f32 v[24:25], v[24:25], v[176:177] op_sel_hi:[1,0]
	v_pk_mul_f32 v[22:23], v[22:23], v[176:177] op_sel_hi:[1,0]
	v_pk_mul_f32 v[20:21], v[20:21], v[176:177] op_sel_hi:[1,0]
	v_pk_mul_f32 v[18:19], v[18:19], v[176:177] op_sel_hi:[1,0]
	v_pk_mul_f32 v[16:17], v[16:17], v[176:177] op_sel_hi:[1,0]
	v_pk_mul_f32 v[14:15], v[14:15], v[176:177] op_sel_hi:[1,0]
	v_pk_mul_f32 v[12:13], v[12:13], v[176:177] op_sel_hi:[1,0]
	v_pk_mul_f32 v[10:11], v[10:11], v[176:177] op_sel_hi:[1,0]
	v_pk_mul_f32 v[8:9], v[8:9], v[176:177] op_sel_hi:[1,0]
	v_pk_mul_f32 v[6:7], v[6:7], v[176:177] op_sel_hi:[1,0]
	v_pk_mul_f32 v[4:5], v[4:5], v[176:177] op_sel_hi:[1,0]
	v_pk_mul_f32 v[2:3], v[2:3], v[176:177] op_sel_hi:[1,0]
	v_pk_mul_f32 v[0:1], v[0:1], v[176:177] op_sel_hi:[1,0]
	v_pk_mul_f32 v[62:63], v[62:63], v[176:177] op_sel_hi:[1,0]
	v_pk_mul_f32 v[60:61], v[60:61], v[176:177] op_sel_hi:[1,0]
	v_pk_mul_f32 v[58:59], v[58:59], v[176:177] op_sel_hi:[1,0]
	v_pk_mul_f32 v[56:57], v[56:57], v[176:177] op_sel_hi:[1,0]
	v_pk_mul_f32 v[54:55], v[54:55], v[176:177] op_sel_hi:[1,0]
	v_pk_mul_f32 v[52:53], v[52:53], v[176:177] op_sel_hi:[1,0]
	v_pk_mul_f32 v[50:51], v[50:51], v[176:177] op_sel_hi:[1,0]
	v_pk_mul_f32 v[48:49], v[48:49], v[176:177] op_sel_hi:[1,0]
	v_mul_f32_e32 v172, v172, v176

.Latt_b_bar:
	s_waitcnt lgkmcnt(0)
	s_barrier
	s_cmp_gt_i32 s86, s9
	s_cbranch_scc1 .LBB0_241
	s_cmp_ge_i32 s86, s9
	s_cbranch_scc1 .Latt_b_pvonly
	s_mul_i32 s4, s69, 0x5000
	v_add_u32_e32 v205, s4, v165
	v_add_u32_e32 v206, s28, v192
	ds_read_b64_tr_b16 v[96:97], v205 offset:34816
	ds_read_b64_tr_b16 v[98:99], v205 offset:37376
	ds_read_b64_tr_b16 v[100:101], v205 offset:39936
	ds_read_b64_tr_b16 v[102:103], v205 offset:42496
	ds_read_b64_tr_b16 v[104:105], v205 offset:45056
	ds_read_b64_tr_b16 v[106:107], v205 offset:47616
	ds_read_b64_tr_b16 v[108:109], v205 offset:50176
	ds_read_b64_tr_b16 v[110:111], v205 offset:52736
	ds_read_b64_tr_b16 v[176:177], v205 offset:34880
	ds_read_b64_tr_b16 v[178:179], v205 offset:37440
	ds_read_b64_tr_b16 v[180:181], v205 offset:40000
	ds_read_b64_tr_b16 v[182:183], v205 offset:42560
	ds_read_b64_tr_b16 v[184:185], v205 offset:45120
	ds_read_b64_tr_b16 v[186:187], v205 offset:47680
	s_setprio 1
	s_waitcnt lgkmcnt(12)
	v_mfma_f32_32x32x16_bf16 v[32:47], v[96:99], v[80:83], v[32:47]
	ds_read_b64_tr_b16 v[96:97], v205 offset:50240
	ds_read_b64_tr_b16 v[98:99], v205 offset:52800
	s_waitcnt lgkmcnt(12)
	v_mfma_f32_32x32x16_bf16 v[32:47], v[100:103], v[84:87], v[32:47]
	ds_read_b64_tr_b16 v[100:101], v205 offset:34944
	ds_read_b64_tr_b16 v[102:103], v205 offset:37504
	s_waitcnt lgkmcnt(12)
	v_mfma_f32_32x32x16_bf16 v[32:47], v[104:107], v[88:91], v[32:47]
	ds_read_b64_tr_b16 v[104:105], v205 offset:40064
	ds_read_b64_tr_b16 v[106:107], v205 offset:42624
	s_waitcnt lgkmcnt(12)
	v_mfma_f32_32x32x16_bf16 v[32:47], v[108:111], v[92:95], v[32:47]
	ds_read_b64_tr_b16 v[108:109], v205 offset:45184
	ds_read_b64_tr_b16 v[110:111], v205 offset:47744
	s_waitcnt lgkmcnt(12)
	v_mfma_f32_32x32x16_bf16 v[16:31], v[176:179], v[80:83], v[16:31]
	ds_read_b64_tr_b16 v[176:177], v205 offset:50304
	ds_read_b64_tr_b16 v[178:179], v205 offset:52864
	s_waitcnt lgkmcnt(12)
	v_mfma_f32_32x32x16_bf16 v[16:31], v[180:183], v[84:87], v[16:31]
	ds_read_b64_tr_b16 v[180:181], v205 offset:35008
	ds_read_b64_tr_b16 v[182:183], v205 offset:37568
	s_waitcnt lgkmcnt(12)
	v_mfma_f32_32x32x16_bf16 v[16:31], v[184:187], v[88:91], v[16:31]
	ds_read_b64_tr_b16 v[184:185], v205 offset:40128
	ds_read_b64_tr_b16 v[186:187], v205 offset:42688
	s_waitcnt lgkmcnt(12)
	v_mfma_f32_32x32x16_bf16 v[16:31], v[96:99], v[92:95], v[16:31]
	ds_read_b64_tr_b16 v[96:97], v205 offset:45248
	ds_read_b64_tr_b16 v[98:99], v205 offset:47808
	s_waitcnt lgkmcnt(12)
	v_mfma_f32_32x32x16_bf16 v[0:15], v[100:103], v[80:83], v[0:15]
	ds_read_b64_tr_b16 v[100:101], v205 offset:50368
	ds_read_b64_tr_b16 v[102:103], v205 offset:52928
	s_waitcnt lgkmcnt(12)
	v_mfma_f32_32x32x16_bf16 v[0:15], v[104:107], v[84:87], v[0:15]
	ds_read_b128 v[210:213], v206 offset:8704
	ds_read_b128 v[104:107], v206 offset:8736
	s_waitcnt lgkmcnt(12)
	v_mfma_f32_32x32x16_bf16 v[0:15], v[108:111], v[88:91], v[0:15]
	ds_read_b128 v[108:111], v206 offset:8768
	ds_read_b128 v[188:191], v206
	s_waitcnt lgkmcnt(12)
	v_mfma_f32_32x32x16_bf16 v[0:15], v[176:179], v[92:95], v[0:15]
	ds_read_b128 v[176:179], v206 offset:8800
	ds_read_b128 v[224:227], v206 offset:32
	s_waitcnt lgkmcnt(12)
	v_mfma_f32_32x32x16_bf16 v[48:63], v[180:183], v[80:83], v[48:63]
	ds_read_b128 v[228:231], v206 offset:64
	ds_read_b128 v[248:251], v206 offset:96
	s_waitcnt lgkmcnt(12)
	v_mfma_f32_32x32x16_bf16 v[48:63], v[184:187], v[84:87], v[48:63]
	s_waitcnt lgkmcnt(10)
	v_mfma_f32_32x32x16_bf16 v[48:63], v[96:99], v[88:91], v[48:63]
	s_waitcnt lgkmcnt(8)
	v_mfma_f32_32x32x16_bf16 v[48:63], v[100:103], v[92:95], v[48:63]
	s_waitcnt lgkmcnt(3)
	v_mfma_f32_32x32x16_bf16 v[80:95], v[210:213], v[112:115], v[64:79]
	v_mfma_f32_32x32x16_bf16 v[80:95], v[104:107], v[116:119], v[80:95]
	v_mfma_f32_32x32x16_bf16 v[80:95], v[108:111], v[120:123], v[80:95]
	v_mfma_f32_32x32x16_bf16 v[80:95], v[176:179], v[124:127], v[80:95]
	s_waitcnt lgkmcnt(0)
	v_mfma_f32_32x32x16_bf16 v[96:111], v[188:191], v[112:115], v[64:79]
	v_mfma_f32_32x32x16_bf16 v[96:111], v[224:227], v[116:119], v[96:111]
	v_mfma_f32_32x32x16_bf16 v[96:111], v[228:231], v[120:123], v[96:111]
	v_mfma_f32_32x32x16_bf16 v[96:111], v[248:251], v[124:127], v[96:111]
	s_setprio 0
	s_cmp_gt_i32 s33, 3
	s_cbranch_scc1 .LBB0_241
	s_waitcnt lgkmcnt(0)
	s_add_i32 s4, s68, 0x100
	v_add_u32_e32 v205, s4, v204
	v_add_u32_e32 v176, 0x17d00, v205
	v_add_u32_e32 v178, 0x17d80, v205
	ds_read2_b32 v[176:177], v176 offset1:1
	ds_read2_b32 v[178:179], v178 offset1:1
	v_add_u32_e32 v180, 0x17d08, v205
	v_add_u32_e32 v182, 0x17d88, v205
	v_add_u32_e32 v184, 0x17d20, v205
	v_add_u32_e32 v186, 0x17da0, v205
	v_add_u32_e32 v188, 0x17d28, v205
	v_add_u32_e32 v190, 0x17da8, v205
	v_add_u32_e32 v206, 0x17d40, v205
	v_add_u32_e32 v210, 0x17dc0, v205
	v_add_u32_e32 v212, 0x17d48, v205
	v_add_u32_e32 v221, 0x17dc8, v205
	ds_read2_b32 v[180:181], v180 offset1:1
	ds_read2_b32 v[182:183], v182 offset1:1
	ds_read2_b32 v[184:185], v184 offset1:1
	ds_read2_b32 v[186:187], v186 offset1:1
	ds_read2_b32 v[188:189], v188 offset1:1
	ds_read2_b32 v[190:191], v190 offset1:1
	ds_read2_b32 v[206:207], v206 offset1:1
	ds_read2_b32 v[210:211], v210 offset1:1
	ds_read2_b32 v[212:213], v212 offset1:1
	ds_read2_b32 v[224:225], v221 offset1:1
	v_add_u32_e32 v221, 0x17d60, v205
	v_add_u32_e32 v223, 0x17de0, v205
	ds_read2_b32 v[226:227], v221 offset1:1
	ds_read2_b32 v[228:229], v223 offset1:1
	v_add_u32_e32 v221, 0x17d68, v205
	v_add_u32_e32 v205, 0x17de8, v205
	ds_read2_b32 v[230:231], v221 offset1:1
	s_waitcnt lgkmcnt(14)
	v_pk_add_f32 v[96:97], v[96:97], v[176:177]
	ds_read2_b32 v[176:177], v205 offset1:1
	s_waitcnt lgkmcnt(3)
	v_pk_add_f32 v[108:109], v[108:109], v[226:227]
	v_pk_add_f32 v[106:107], v[106:107], v[212:213]
	s_waitcnt lgkmcnt(1)
	v_pk_add_f32 v[110:111], v[110:111], v[230:231]
	v_pk_add_f32 v[104:105], v[104:105], v[206:207]
	v_pk_add_f32 v[102:103], v[102:103], v[188:189]
	v_pk_add_f32 v[100:101], v[100:101], v[184:185]
	v_pk_add_f32 v[98:99], v[98:99], v[180:181]
	s_waitcnt lgkmcnt(0)
	v_pk_add_f32 v[94:95], v[94:95], v[176:177]
	v_pk_add_f32 v[92:93], v[92:93], v[228:229]
	v_pk_add_f32 v[90:91], v[90:91], v[224:225]
	v_pk_add_f32 v[88:89], v[88:89], v[210:211]
	v_pk_add_f32 v[86:87], v[86:87], v[190:191]
	v_pk_add_f32 v[84:85], v[84:85], v[186:187]
	v_pk_add_f32 v[82:83], v[82:83], v[182:183]
	v_pk_add_f32 v[80:81], v[80:81], v[178:179]
	s_nop 0
	s_branch .LBB0_241

.Latt_a:
	s_mul_i32 s4, s87, 0x5000
	v_add_u32_e32 v205, s4, v165
	v_add_u32_e32 v206, s5, v192
	ds_read_b64_tr_b16 v[96:97], v205 offset:34816
	ds_read_b64_tr_b16 v[98:99], v205 offset:37376
	ds_read_b64_tr_b16 v[100:101], v205 offset:39936
	ds_read_b64_tr_b16 v[102:103], v205 offset:42496
	ds_read_b64_tr_b16 v[104:105], v205 offset:45056
	ds_read_b64_tr_b16 v[106:107], v205 offset:47616
	ds_read_b64_tr_b16 v[108:109], v205 offset:50176
	ds_read_b64_tr_b16 v[110:111], v205 offset:52736
	ds_read_b64_tr_b16 v[176:177], v205 offset:34880
	ds_read_b64_tr_b16 v[178:179], v205 offset:37440
	ds_read_b64_tr_b16 v[180:181], v205 offset:40000
	ds_read_b64_tr_b16 v[182:183], v205 offset:42560
	ds_read_b64_tr_b16 v[184:185], v205 offset:45120
	ds_read_b64_tr_b16 v[186:187], v205 offset:47680
	s_setprio 1
	s_waitcnt lgkmcnt(12)
	v_mfma_f32_32x32x16_bf16 v[32:47], v[96:99], v[80:83], v[32:47]
	ds_read_b64_tr_b16 v[96:97], v205 offset:50240
	ds_read_b64_tr_b16 v[98:99], v205 offset:52800
	s_waitcnt lgkmcnt(12)
	v_mfma_f32_32x32x16_bf16 v[32:47], v[100:103], v[84:87], v[32:47]
	ds_read_b64_tr_b16 v[100:101], v205 offset:34944
	ds_read_b64_tr_b16 v[102:103], v205 offset:37504
	s_waitcnt lgkmcnt(12)
	v_mfma_f32_32x32x16_bf16 v[32:47], v[104:107], v[88:91], v[32:47]
	ds_read_b64_tr_b16 v[104:105], v205 offset:40064
	ds_read_b64_tr_b16 v[106:107], v205 offset:42624
	s_waitcnt lgkmcnt(12)
	v_mfma_f32_32x32x16_bf16 v[32:47], v[108:111], v[92:95], v[32:47]
	ds_read_b64_tr_b16 v[108:109], v205 offset:45184
	ds_read_b64_tr_b16 v[110:111], v205 offset:47744
	s_waitcnt lgkmcnt(12)
	v_mfma_f32_32x32x16_bf16 v[16:31], v[176:179], v[80:83], v[16:31]
	ds_read_b64_tr_b16 v[176:177], v205 offset:50304
	ds_read_b64_tr_b16 v[178:179], v205 offset:52864
	s_waitcnt lgkmcnt(12)
	v_mfma_f32_32x32x16_bf16 v[16:31], v[180:183], v[84:87], v[16:31]
	ds_read_b64_tr_b16 v[180:181], v205 offset:35008
	ds_read_b64_tr_b16 v[182:183], v205 offset:37568
	s_waitcnt lgkmcnt(12)
	v_mfma_f32_32x32x16_bf16 v[16:31], v[184:187], v[88:91], v[16:31]
	ds_read_b64_tr_b16 v[184:185], v205 offset:40128
	ds_read_b64_tr_b16 v[186:187], v205 offset:42688
	s_waitcnt lgkmcnt(12)
	v_mfma_f32_32x32x16_bf16 v[16:31], v[96:99], v[92:95], v[16:31]
	ds_read_b64_tr_b16 v[96:97], v205 offset:45248
	ds_read_b64_tr_b16 v[98:99], v205 offset:47808
	s_waitcnt lgkmcnt(12)
	v_mfma_f32_32x32x16_bf16 v[0:15], v[100:103], v[80:83], v[0:15]
	ds_read_b64_tr_b16 v[100:101], v205 offset:50368
	ds_read_b64_tr_b16 v[102:103], v205 offset:52928
	s_waitcnt lgkmcnt(12)
	v_mfma_f32_32x32x16_bf16 v[0:15], v[104:107], v[84:87], v[0:15]
	ds_read_b128 v[210:213], v206 offset:8704
	ds_read_b128 v[104:107], v206 offset:8736
	s_waitcnt lgkmcnt(12)
	v_mfma_f32_32x32x16_bf16 v[0:15], v[108:111], v[88:91], v[0:15]
	ds_read_b128 v[108:111], v206 offset:8768
	ds_read_b128 v[188:191], v206
	s_waitcnt lgkmcnt(12)
	v_mfma_f32_32x32x16_bf16 v[0:15], v[176:179], v[92:95], v[0:15]
	ds_read_b128 v[176:179], v206 offset:8800
	ds_read_b128 v[224:227], v206 offset:32
	s_waitcnt lgkmcnt(12)
	v_mfma_f32_32x32x16_bf16 v[48:63], v[180:183], v[80:83], v[48:63]
	ds_read_b128 v[228:231], v206 offset:64
	ds_read_b128 v[248:251], v206 offset:96
	s_waitcnt lgkmcnt(12)
	v_mfma_f32_32x32x16_bf16 v[48:63], v[184:187], v[84:87], v[48:63]
	s_waitcnt lgkmcnt(10)
	v_mfma_f32_32x32x16_bf16 v[48:63], v[96:99], v[88:91], v[48:63]
	s_waitcnt lgkmcnt(8)
	v_mfma_f32_32x32x16_bf16 v[48:63], v[100:103], v[92:95], v[48:63]
	s_waitcnt lgkmcnt(3)
	v_mfma_f32_32x32x16_bf16 v[80:95], v[210:213], v[112:115], v[64:79]
	v_mfma_f32_32x32x16_bf16 v[80:95], v[104:107], v[116:119], v[80:95]
	v_mfma_f32_32x32x16_bf16 v[80:95], v[108:111], v[120:123], v[80:95]
	v_mfma_f32_32x32x16_bf16 v[80:95], v[176:179], v[124:127], v[80:95]
	s_waitcnt lgkmcnt(0)
	v_mfma_f32_32x32x16_bf16 v[96:111], v[188:191], v[112:115], v[64:79]
	v_mfma_f32_32x32x16_bf16 v[96:111], v[224:227], v[116:119], v[96:111]
	v_mfma_f32_32x32x16_bf16 v[96:111], v[228:231], v[120:123], v[96:111]
	v_mfma_f32_32x32x16_bf16 v[96:111], v[248:251], v[124:127], v[96:111]
	s_setprio 0
	s_cmp_gt_i32 s33, 2
	s_cbranch_scc1 .Latt_a_stg
	s_waitcnt lgkmcnt(0)
	v_add_u32_e32 v205, s68, v204
	v_add_u32_e32 v176, 0x17d00, v205
	v_add_u32_e32 v178, 0x17d80, v205
	ds_read2_b32 v[176:177], v176 offset1:1
	ds_read2_b32 v[178:179], v178 offset1:1
	v_add_u32_e32 v180, 0x17d08, v205
	v_add_u32_e32 v182, 0x17d88, v205
	v_add_u32_e32 v184, 0x17d20, v205
	v_add_u32_e32 v186, 0x17da0, v205
	v_add_u32_e32 v188, 0x17d28, v205
	v_add_u32_e32 v190, 0x17da8, v205
	v_add_u32_e32 v206, 0x17d40, v205
	v_add_u32_e32 v210, 0x17dc0, v205
	v_add_u32_e32 v212, 0x17d48, v205
	v_add_u32_e32 v221, 0x17dc8, v205
	ds_read2_b32 v[180:181], v180 offset1:1
	ds_read2_b32 v[182:183], v182 offset1:1
	ds_read2_b32 v[184:185], v184 offset1:1
	ds_read2_b32 v[186:187], v186 offset1:1
	ds_read2_b32 v[188:189], v188 offset1:1
	ds_read2_b32 v[190:191], v190 offset1:1
	ds_read2_b32 v[206:207], v206 offset1:1
	ds_read2_b32 v[210:211], v210 offset1:1
	ds_read2_b32 v[212:213], v212 offset1:1
	ds_read2_b32 v[224:225], v221 offset1:1
	v_add_u32_e32 v221, 0x17d60, v205
	v_add_u32_e32 v223, 0x17de0, v205
	ds_read2_b32 v[226:227], v221 offset1:1
	ds_read2_b32 v[228:229], v223 offset1:1
	v_add_u32_e32 v221, 0x17d68, v205
	v_add_u32_e32 v205, 0x17de8, v205
	ds_read2_b32 v[230:231], v221 offset1:1
	s_waitcnt lgkmcnt(14)
	v_pk_add_f32 v[96:97], v[96:97], v[176:177]
	ds_read2_b32 v[176:177], v205 offset1:1
	s_waitcnt lgkmcnt(3)
	v_pk_add_f32 v[108:109], v[108:109], v[226:227]
	v_pk_add_f32 v[106:107], v[106:107], v[212:213]
	s_waitcnt lgkmcnt(1)
	v_pk_add_f32 v[110:111], v[110:111], v[230:231]
	v_pk_add_f32 v[104:105], v[104:105], v[206:207]
	v_pk_add_f32 v[102:103], v[102:103], v[188:189]
	v_pk_add_f32 v[100:101], v[100:101], v[184:185]
	v_pk_add_f32 v[98:99], v[98:99], v[180:181]
	s_waitcnt lgkmcnt(0)
	v_pk_add_f32 v[94:95], v[94:95], v[176:177]
	v_pk_add_f32 v[92:93], v[92:93], v[228:229]
	v_pk_add_f32 v[90:91], v[90:91], v[224:225]
	v_pk_add_f32 v[88:89], v[88:89], v[210:211]
	v_pk_add_f32 v[86:87], v[86:87], v[190:191]
	v_pk_add_f32 v[84:85], v[84:85], v[186:187]
	v_pk_add_f32 v[82:83], v[82:83], v[182:183]
	v_pk_add_f32 v[80:81], v[80:81], v[178:179]
	s_nop 0
.Latt_a_stg:
	s_cmp_ge_u32 s65, s66
	s_cbranch_scc1 .Latt_a_bar
	v_add_u32_e32 v176, s28, v157
	s_waitcnt vmcnt(3)
	ds_write_b128 v176, v[128:131]
	v_add_u32_e32 v176, s29, v159
	s_waitcnt vmcnt(2)
	ds_write_b128 v176, v[132:135] offset:34816
	v_add_u32_e32 v176, s28, v161
	s_waitcnt vmcnt(1)
	ds_write_b128 v176, v[136:139]
	v_add_u32_e32 v176, s29, v163
	s_cmp_ge_u32 s86, s8
	s_waitcnt vmcnt(0)
	ds_write_b128 v176, v[140:143] offset:34816
	s_cbranch_scc1 .Latt_a_bar
	global_load_dwordx4 v[128:131], v232, s[92:93]
	global_load_dwordx4 v[132:135], v232, s[80:81]
	global_load_dwordx4 v[136:139], v233, s[92:93]
	global_load_dwordx4 v[140:143], v233, s[80:81]
.Latt_a_bar:
	s_waitcnt lgkmcnt(0)
	s_barrier
	s_nop 9
	v_max_f32_e32 v176, v96, v80
	v_max3_f32 v177, v81, v98, v82
	v_max3_f32 v176, v176, v97, v99
	v_max3_f32 v177, v177, v100, v84
	v_max3_f32 v176, v176, v83, v101
	v_max3_f32 v177, v177, v102, v86
	v_max3_f32 v176, v176, v85, v103
	v_max3_f32 v177, v177, v104, v88
	v_max3_f32 v176, v176, v87, v105
	v_max3_f32 v177, v177, v106, v90
	v_max3_f32 v176, v176, v89, v107
	v_max3_f32 v177, v177, v108, v92
	v_max3_f32 v176, v176, v91, v109
	v_max3_f32 v177, v177, v110, v94
	v_max3_f32 v176, v176, v93, v111
	v_max3_f32 v176, v176, v95, v177
	v_mov_b32_e32 v177, v176
	s_nop 1
	v_permlane32_swap_b32_e32 v176, v177
	v_max_f32_e32 v176, v176, v177
	v_cmp_lt_f32_e32 vcc, 0x41000000, v176
	s_cbranch_vccz .Latt_a_exp
	v_max_f32_e32 v64, v176, v176
	v_max_f32_e32 v66, 0, v64
	v_exp_f32_e64 v176, -v66
	v_add_f32_e32 v173, v173, v66
	v_xor_b32_e32 v64, 0x80000000, v173
	v_pk_add_f32 v[96:97], v[96:97], v[66:67] op_sel_hi:[1,0] neg_lo:[0,1] neg_hi:[0,1]
	v_pk_add_f32 v[80:81], v[80:81], v[66:67] op_sel_hi:[1,0] neg_lo:[0,1] neg_hi:[0,1]
	v_pk_add_f32 v[98:99], v[98:99], v[66:67] op_sel_hi:[1,0] neg_lo:[0,1] neg_hi:[0,1]
	v_pk_add_f32 v[82:83], v[82:83], v[66:67] op_sel_hi:[1,0] neg_lo:[0,1] neg_hi:[0,1]
	v_pk_add_f32 v[100:101], v[100:101], v[66:67] op_sel_hi:[1,0] neg_lo:[0,1] neg_hi:[0,1]
	v_pk_add_f32 v[84:85], v[84:85], v[66:67] op_sel_hi:[1,0] neg_lo:[0,1] neg_hi:[0,1]
	v_pk_add_f32 v[102:103], v[102:103], v[66:67] op_sel_hi:[1,0] neg_lo:[0,1] neg_hi:[0,1]
	v_pk_add_f32 v[86:87], v[86:87], v[66:67] op_sel_hi:[1,0] neg_lo:[0,1] neg_hi:[0,1]
	v_pk_add_f32 v[104:105], v[104:105], v[66:67] op_sel_hi:[1,0] neg_lo:[0,1] neg_hi:[0,1]
	v_pk_add_f32 v[88:89], v[88:89], v[66:67] op_sel_hi:[1,0] neg_lo:[0,1] neg_hi:[0,1]
	v_pk_add_f32 v[106:107], v[106:107], v[66:67] op_sel_hi:[1,0] neg_lo:[0,1] neg_hi:[0,1]
	v_pk_add_f32 v[90:91], v[90:91], v[66:67] op_sel_hi:[1,0] neg_lo:[0,1] neg_hi:[0,1]
	v_pk_add_f32 v[108:109], v[108:109], v[66:67] op_sel_hi:[1,0] neg_lo:[0,1] neg_hi:[0,1]
	v_pk_add_f32 v[92:93], v[92:93], v[66:67] op_sel_hi:[1,0] neg_lo:[0,1] neg_hi:[0,1]
	v_pk_add_f32 v[110:111], v[110:111], v[66:67] op_sel_hi:[1,0] neg_lo:[0,1] neg_hi:[0,1]
	v_pk_add_f32 v[94:95], v[94:95], v[66:67] op_sel_hi:[1,0] neg_lo:[0,1] neg_hi:[0,1]
	v_mov_b32_e32 v65, v64
	v_mov_b32_e32 v66, v64
	v_mov_b32_e32 v67, v64
	v_mov_b32_e32 v68, v64
	v_mov_b32_e32 v69, v64
	v_mov_b32_e32 v70, v64
	v_mov_b32_e32 v71, v64
	v_mov_b32_e32 v72, v64
	v_mov_b32_e32 v73, v64
	v_mov_b32_e32 v74, v64
	v_mov_b32_e32 v75, v64
	v_mov_b32_e32 v76, v64
	v_mov_b32_e32 v77, v64
	v_mov_b32_e32 v78, v64
	v_mov_b32_e32 v79, v64
	v_pk_mul_f32 v[46:47], v[46:47], v[176:177] op_sel_hi:[1,0]
	v_pk_mul_f32 v[44:45], v[44:45], v[176:177] op_sel_hi:[1,0]
	v_pk_mul_f32 v[42:43], v[42:43], v[176:177] op_sel_hi:[1,0]
	v_pk_mul_f32 v[40:41], v[40:41], v[176:177] op_sel_hi:[1,0]
	v_pk_mul_f32 v[38:39], v[38:39], v[176:177] op_sel_hi:[1,0]
	v_pk_mul_f32 v[36:37], v[36:37], v[176:177] op_sel_hi:[1,0]
	v_pk_mul_f32 v[34:35], v[34:35], v[176:177] op_sel_hi:[1,0]
	v_pk_mul_f32 v[32:33], v[32:33], v[176:177] op_sel_hi:[1,0]
	v_pk_mul_f32 v[30:31], v[30:31], v[176:177] op_sel_hi:[1,0]
	v_pk_mul_f32 v[28:29], v[28:29], v[176:177] op_sel_hi:[1,0]
	v_pk_mul_f32 v[26:27], v[26:27], v[176:177] op_sel_hi:[1,0]
	v_pk_mul_f32 v[24:25], v[24:25], v[176:177] op_sel_hi:[1,0]
	v_pk_mul_f32 v[22:23], v[22:23], v[176:177] op_sel_hi:[1,0]
	v_pk_mul_f32 v[20:21], v[20:21], v[176:177] op_sel_hi:[1,0]
	v_pk_mul_f32 v[18:19], v[18:19], v[176:177] op_sel_hi:[1,0]
	v_pk_mul_f32 v[16:17], v[16:17], v[176:177] op_sel_hi:[1,0]
	v_pk_mul_f32 v[14:15], v[14:15], v[176:177] op_sel_hi:[1,0]
	v_pk_mul_f32 v[12:13], v[12:13], v[176:177] op_sel_hi:[1,0]
	v_pk_mul_f32 v[10:11], v[10:11], v[176:177] op_sel_hi:[1,0]
	v_pk_mul_f32 v[8:9], v[8:9], v[176:177] op_sel_hi:[1,0]
	v_pk_mul_f32 v[6:7], v[6:7], v[176:177] op_sel_hi:[1,0]
	v_pk_mul_f32 v[4:5], v[4:5], v[176:177] op_sel_hi:[1,0]
	v_pk_mul_f32 v[2:3], v[2:3], v[176:177] op_sel_hi:[1,0]
	v_pk_mul_f32 v[0:1], v[0:1], v[176:177] op_sel_hi:[1,0]
	v_pk_mul_f32 v[62:63], v[62:63], v[176:177] op_sel_hi:[1,0]
	v_pk_mul_f32 v[60:61], v[60:61], v[176:177] op_sel_hi:[1,0]
	v_pk_mul_f32 v[58:59], v[58:59], v[176:177] op_sel_hi:[1,0]
	v_pk_mul_f32 v[56:57], v[56:57], v[176:177] op_sel_hi:[1,0]
	v_pk_mul_f32 v[54:55], v[54:55], v[176:177] op_sel_hi:[1,0]
	v_pk_mul_f32 v[52:53], v[52:53], v[176:177] op_sel_hi:[1,0]
	v_pk_mul_f32 v[50:51], v[50:51], v[176:177] op_sel_hi:[1,0]
	v_pk_mul_f32 v[48:49], v[48:49], v[176:177] op_sel_hi:[1,0]
	v_mul_f32_e32 v172, v172, v176

.LBB0_241:
	s_add_i32 s4, s69, 1
	s_cmp_lg_u32 s69, 2
	s_cselect_b32 s4, s4, 0
	s_addk_i32 s68, 0x100
	s_add_i32 s65, s65, 1
	s_add_i32 s33, s33, -1
	s_add_u32 s80, s80, 0x20000
	s_addc_u32 s81, s81, 0
	s_add_u32 s92, s92, 0x20000
	s_addc_u32 s93, s93, 0
	s_cmp_eq_u32 s21, s68
	s_cbranch_scc1 .LBB0_243
	s_mov_b32 s87, s69
	s_branch .LBB0_228

.LBB0_254:
	s_add_u32 s92, s90, 0x1400000
	s_addc_u32 s93, s91, 0
	v_readlane_b32 s48, v255, 0
	s_mov_b64 s[4:5], 0
	v_readlane_b32 s49, v255, 1
	v_readlane_b32 s33, v255, 2
	s_movk_i32 s58, 0x3ff
	s_movk_i32 s59, 0x204
	s_mov_b32 s60, 0x3e38aa3b
